# scan: producer waves run at s_setprio 2 for the unit (consumer waves have slack)
# speedup vs baseline: 1.0108x; 1.0078x over previous
; #define LAS __attribute__((address_space(3)))
; __device__ __forceinline__ void scan_unit_mfma(const TI ti, CArgs& a, int l, int u, bool ctx_out, unsigned char* ldsg) {
;     ...
;     } else {
;         const int p = w - 2, ch = hh * 64 + lane;
;         const bf16_t* RW = (const bf16_t*)(a.ws + WS_RW);
;         const bf16_t* DEC = (const bf16_t*)(a.ws + (d ? WS_DEC1 : WS_GV));
;         const bf16_t* AA = (const bf16_t*)(a.ws + (d ? WS_AA1 : WS_AA0));
;         const float* mu = a.in[16] + l * 3488;
;         const float mur = mu[ch], muk = mu[1024 + ch], muv = mu[2048 + ch], kkg = a.in[22][l * 1024 + ch], kag = a.in[23][l * 1024 + ch];
;         LAS unsigned char* buf = L + p * BUFB;
;         LAS bf16_t* AR = (LAS bf16_t*)(buf + O_AR); LAS bf16_t* BK = (LAS bf16_t*)(buf + O_BK); LAS bf16_t* BKT = (LAS bf16_t*)(buf + O_BKT); LAS bf16_t* VTT = (LAS bf16_t*)(buf + O_VTT);
;         LAS float* PC = (LAS float*)(buf + O_PC);
;         constexpr int NSTEP = (NCH / RING) * 4;
;         unsigned nxt[4][11], cur[4][11];
; __global__ void __launch_bounds__(512, 2) mega_fwd(Args a_) {
;     ...
;                 if constexpr (PH_ON(4)) { for (int u = ti.bid; u < 256; u += ti.nblk) scan_unit_mfma(ti, a, l, u, ctx_out, lds); }
.LBB0_303:
	s_setprio 0
	s_add_i32 s11, s11, s0
	s_cmpk_gt_i32 s11, 0xff
	s_waitcnt vmcnt(0) lgkmcnt(0)
	s_barrier
	s_cbranch_scc1 .LBB0_328
.LBB0_304:
	v_readfirstlane_b32 s1, v178
	s_ashr_i32 s17, s1, 6
	s_ashr_i32 s16, s11, 5
	s_bfe_u32 s14, s11, 0x40001
	s_and_b32 s18, s11, 1
	s_cmp_gt_i32 s17, 1
	s_mov_b64 s[4:5], -1
	s_cbranch_scc0 .LBB0_319
	s_setprio 2
	s_lshr_b32 s5, s1, 6
	s_add_i32 s27, s17, -2
	s_lshl_b32 s4, s14, 6
	s_load_dwordx2 s[62:63], s[74:75], 0x110
	s_cmp_eq_u32 s18, 0
	s_cselect_b64 s[60:61], -1, 0
	s_and_b64 s[6:7], s[60:61], exec
	s_mov_b32 s1, 0x8200000
	s_cselect_b32 s1, s1, 0x20e00000
	s_waitcnt lgkmcnt(0)
	s_add_u32 s34, s62, s1
	s_addc_u32 s35, s63, 0
	s_and_b64 s[6:7], s[60:61], exec
	s_load_dwordx2 s[6:7], s[74:75], 0x80
	s_load_dwordx4 s[76:79], s[74:75], 0xb0
	s_mov_b32 s1, 0x23200000
	s_cselect_b32 s1, s1, 0x25600000
	s_add_u32 s37, s62, s1
	s_addc_u32 s39, s63, 0
	v_or_b32_e32 v4, s4, v180
	s_waitcnt lgkmcnt(0)
; #define LAS __attribute__((address_space(3)))
; __device__ __forceinline__ void scan_unit_mfma(const TI ti, CArgs& a, int l, int u, bool ctx_out, unsigned char* ldsg) {
;     ...
;         const int p = w - 2, ch = hh * 64 + lane;
;         const bf16_t* RW = (const bf16_t*)(a.ws + WS_RW);
;         const bf16_t* DEC = (const bf16_t*)(a.ws + (d ? WS_DEC1 : WS_GV));
;         const bf16_t* AA = (const bf16_t*)(a.ws + (d ? WS_AA1 : WS_AA0));
;         const float* mu = a.in[16] + l * 3488;
;         const float mur = mu[ch], muk = mu[1024 + ch], muv = mu[2048 + ch], kkg = a.in[22][l * 1024 + ch], kag = a.in[23][l * 1024 + ch];
;         LAS unsigned char* buf = L + p * BUFB;
;         LAS bf16_t* AR = (LAS bf16_t*)(buf + O_AR); LAS bf16_t* BK = (LAS bf16_t*)(buf + O_BK); LAS bf16_t* BKT = (LAS bf16_t*)(buf + O_BKT); LAS bf16_t* VTT = (LAS bf16_t*)(buf + O_VTT);
;         LAS float* PC = (LAS float*)(buf + O_PC);
;         constexpr int NSTEP = (NCH / RING) * 4;
;         unsigned nxt[4][11], cur[4][11];
;     ...
;         SC2_LOAD(0);
	s_add_u32 s6, s6, s96
	s_addc_u32 s7, s7, s97
	v_lshlrev_b32_e32 v0, 2, v4
	v_lshl_add_u64 v[2:3], s[6:7], 0, v[0:1]
	v_add_co_u32_e32 v2, vcc, s93, v2
	v_readlane_b32 s1, v255, 57
	s_nop 0
	v_addc_co_u32_e32 v3, vcc, 0, v3, vcc
	global_load_dword v0, v0, s[6:7]
	s_nop 0
	global_load_dword v18, v[2:3], off offset:-4096
	global_load_dword v19, v[2:3], off
	v_or_b32_e32 v2, s1, v4
	v_ashrrev_i32_e32 v3, 31, v2
	v_lshlrev_b64 v[2:3], 2, v[2:3]
	v_lshl_add_u64 v[4:5], s[76:77], 0, v[2:3]
	v_lshl_add_u64 v[2:3], s[78:79], 0, v[2:3]
	s_mul_i32 s1, s27, 0x5100
	s_lshl_b32 s72, s16, 8
	global_load_dword v21, v[2:3], off
	s_add_i32 s62, s1, 0
	v_sub_co_u32_e64 v2, s[6:7], s17, 18
	s_addk_i32 s72, 0x4000
	s_lshl_b32 s73, s16, 11
	s_and_b64 s[6:7], s[6:7], exec
	v_readfirstlane_b32 s1, v2
	s_movk_i32 s90, 0x800
	s_cselect_b32 s1, s27, s1
	s_cselect_b32 s36, 0x100, s90
	s_cselect_b32 s33, s72, s73
	s_lshl_b32 s6, s14, 7
	v_readlane_b32 s3, v255, 54
	s_add_u32 s79, s3, s6
	v_readlane_b32 s3, v255, 56
	s_addc_u32 s81, s3, 0
	s_lshl_b32 s63, s1, 4
	s_not_b32 s1, s63
	s_add_i32 s7, s36, -1
	s_add_i32 s1, s36, s1
	s_and_b64 s[76:77], s[60:61], exec
	s_cselect_b32 s1, s63, s1
	s_add_i32 s76, s1, s33
	s_ashr_i32 s77, s76, 31
	s_mul_i32 s10, s76, 0x1c00
	s_mul_hi_i32 s3, s76, 0x1c00
	s_add_u32 s10, s79, s10
	s_addc_u32 s3, s81, s3
	s_add_u32 s92, s10, 0x800
	s_addc_u32 s93, s3, 0
	s_cmp_gt_i32 s1, 0
	s_cselect_b32 s10, 0xffffe400, 0
	s_cselect_b32 s3, -1, 0
	s_add_u32 s94, s92, s10
	s_addc_u32 s95, s93, s3
	s_cmp_lt_i32 s1, s7
	s_cselect_b32 s1, 0x1c00, 0
	s_add_u32 vcc_lo, s92, s1
	s_addc_u32 vcc_hi, s93, 0
	s_lshl_b64 s[76:77], s[76:77], 11
	s_add_u32 s1, s34, s76
	v_lshlrev_b32_e32 v22, 1, v180
	s_addc_u32 s3, s35, s77
	global_load_dword v20, v[4:5], off
	global_load_ushort v69, v22, s[94:95] offset:-2048
	global_load_ushort v66, v22, s[94:95]
	global_load_ushort v56, v22, s[94:95] offset:2048
	global_load_ushort v71, v22, s[92:93] offset:-2048
	global_load_ushort v70, v22, s[92:93]
	global_load_ushort v68, v22, s[92:93] offset:2048
	global_load_ushort v72, v22, vcc offset:-2048
	global_load_ushort v67, v22, vcc
	global_load_ushort v65, v22, vcc offset:2048
	s_add_u32 s92, s1, s6
	s_addc_u32 s93, s3, 0
	s_add_u32 s1, s37, s76
	s_addc_u32 s3, s39, s77
	s_add_u32 s76, s1, s6
	s_addc_u32 s77, s3, 0
	s_xor_b32 s3, s63, -2
	s_or_b32 s1, s63, 1
	s_add_i32 s3, s3, s36
	global_load_ushort v39, v22, s[92:93]
	global_load_ushort v51, v22, s[76:77]
	s_and_b64 s[76:77], s[60:61], exec
	s_cselect_b32 s1, s1, s3
	s_add_i32 s76, s1, s33
	s_ashr_i32 s77, s76, 31
	s_mul_i32 s10, s76, 0x1c00
	s_mul_hi_i32 s3, s76, 0x1c00
	s_add_u32 s10, s79, s10
	s_addc_u32 s3, s81, s3
	s_add_u32 s92, s10, 0x800
	s_addc_u32 s93, s3, 0
	s_cmp_gt_i32 s1, 0
	s_cselect_b32 s10, 0xffffe400, 0
	s_cselect_b32 s3, -1, 0
	s_add_u32 s94, s92, s10
	s_addc_u32 s95, s93, s3
	s_cmp_lt_i32 s1, s7
	s_cselect_b32 s1, 0x1c00, 0
	s_add_u32 vcc_lo, s92, s1
	s_addc_u32 vcc_hi, s93, 0
	s_lshl_b64 s[76:77], s[76:77], 11
	s_add_u32 s1, s34, s76
	s_addc_u32 s3, s35, s77
	global_load_ushort v52, v22, s[94:95] offset:-2048
	global_load_ushort v44, v22, s[94:95]
	global_load_ushort v35, v22, s[94:95] offset:2048
	global_load_ushort v64, v22, s[92:93] offset:-2048
	global_load_ushort v61, v22, s[92:93]
	global_load_ushort v55, v22, s[92:93] offset:2048
	global_load_ushort v62, v22, vcc offset:-2048
	global_load_ushort v47, v22, vcc
	global_load_ushort v40, v22, vcc offset:2048
	s_add_u32 s92, s1, s6
	s_addc_u32 s93, s3, 0
	s_add_u32 s1, s37, s76
	s_addc_u32 s3, s39, s77
	s_add_u32 s76, s1, s6
	s_addc_u32 s77, s3, 0
	s_xor_b32 s3, s63, -3
	s_or_b32 s1, s63, 2
	s_add_i32 s3, s3, s36
	global_load_ushort v27, v22, s[92:93]
	global_load_ushort v34, v22, s[76:77]
	s_and_b64 s[76:77], s[60:61], exec
	s_cselect_b32 s1, s1, s3
	s_add_i32 s76, s1, s33
	s_ashr_i32 s77, s76, 31
	s_mul_i32 s10, s76, 0x1c00
	s_mul_hi_i32 s3, s76, 0x1c00
	s_add_u32 s10, s79, s10
	s_addc_u32 s3, s81, s3
	s_add_u32 s92, s10, 0x800
	s_addc_u32 s93, s3, 0
	s_cmp_gt_i32 s1, 0
	s_cselect_b32 s10, 0xffffe400, 0
	s_cselect_b32 s3, -1, 0
	s_add_u32 s94, s92, s10
	s_addc_u32 s95, s93, s3
	s_cmp_lt_i32 s1, s7
	s_cselect_b32 s1, 0x1c00, 0
	s_add_u32 vcc_lo, s92, s1
	s_addc_u32 vcc_hi, s93, 0
	s_lshl_b64 s[76:77], s[76:77], 11
	s_add_u32 s1, s34, s76
	s_addc_u32 s3, s35, s77
	global_load_ushort v30, v22, s[94:95] offset:-2048
	global_load_ushort v25, v22, s[94:95]
	global_load_ushort v23, v22, s[94:95] offset:2048
	global_load_ushort v63, v22, s[92:93] offset:-2048
	global_load_ushort v57, v22, s[92:93]
	global_load_ushort v53, v22, s[92:93] offset:2048
	global_load_ushort v59, v22, vcc offset:-2048
	global_load_ushort v45, v22, vcc
	global_load_ushort v37, v22, vcc offset:2048
	s_add_u32 s92, s1, s6
	s_addc_u32 s93, s3, 0
	s_add_u32 s1, s37, s76
	s_addc_u32 s3, s39, s77
	s_add_u32 s76, s1, s6
	s_addc_u32 s77, s3, 0
	s_xor_b32 s3, s63, -4
	s_or_b32 s1, s63, 3
	s_add_i32 s3, s3, s36
	global_load_ushort v41, v22, s[92:93]
	global_load_ushort v49, v22, s[76:77]
	s_and_b64 s[76:77], s[60:61], exec
	s_cselect_b32 s1, s1, s3
	s_add_i32 s76, s1, s33
	s_ashr_i32 s77, s76, 31
	s_mul_i32 s10, s76, 0x1c00
	s_mul_hi_i32 s3, s76, 0x1c00
	s_add_u32 s10, s79, s10
	s_addc_u32 s3, s81, s3
	s_add_u32 s92, s10, 0x800
	s_addc_u32 s93, s3, 0
	s_cmp_gt_i32 s1, 0
	s_cselect_b32 s10, 0xffffe400, 0
	s_cselect_b32 s3, -1, 0
	s_add_u32 s94, s92, s10
	s_addc_u32 s95, s93, s3
	s_cmp_lt_i32 s1, s7
	s_cselect_b32 s1, 0x1c00, 0
	s_add_u32 vcc_lo, s92, s1
	s_addc_u32 vcc_hi, s93, 0
	s_lshl_b64 s[76:77], s[76:77], 11
	s_add_u32 s1, s34, s76
	global_load_ushort v50, v22, s[94:95] offset:-2048
	global_load_ushort v42, v22, s[94:95]
	global_load_ushort v32, v22, s[94:95] offset:2048
	global_load_ushort v58, v22, s[92:93] offset:-2048
	global_load_ushort v54, v22, s[92:93]
	global_load_ushort v48, v22, s[92:93] offset:2048
	global_load_ushort v60, v22, vcc offset:-2048
	global_load_ushort v46, v22, vcc
	global_load_ushort v38, v22, vcc offset:2048
	s_addc_u32 s3, s35, s77
	s_add_u32 s92, s1, s6
	s_addc_u32 s93, s3, 0
	s_add_u32 s1, s37, s76
	s_addc_u32 s3, s39, s77
	s_add_u32 s6, s1, s6
	s_addc_u32 s7, s3, 0
	global_load_ushort v26, v22, s[92:93]
	global_load_ushort v43, v22, s[6:7]
	v_lshlrev_b32_e32 v3, 2, v80
	s_mul_i32 s1, s17, 0x4ec0
	v_add_u32_e32 v2, s62, v85
	v_add3_u32 v24, s62, v88, v3
	v_add_u32_e32 v3, s62, v90
	v_add_u32_e32 v28, s1, v95
	s_mul_i32 s1, s17, 0x50f8
	s_lshl_b32 s3, s17, 2
	s_mov_b32 s9, s67
	s_mov_b32 s76, 0
	s_sub_i32 s77, 0, s17
	s_sub_i32 s78, 1, s5
	s_sub_i32 s92, 1, s17
	v_add_u32_e32 v29, s1, v96
	s_add_i32 s93, s3, -8
	s_sub_i32 s94, 7, s3
	v_add_u32_e32 v31, s1, v97
	v_mov_b32_e32 v74, 1.0
	v_mov_b32_e32 v73, 0
	v_add_u32_e32 v33, v2, v86
	s_lshl_b32 s95, s4, 1
	v_add_u32_e32 v36, v3, v94
	s_branch .LBB0_308
